# SSD pass-B sW section: 48 serialized ds_read_b32 (32 LDS round trips per chunk) replaced by 12 up-front reads
# speedup vs baseline: 1.1689x; 1.0076x over previous
.LBB0_1708:
	ds_read_b32 v139, v215
	ds_read_b128 v[60:63], v157
	ds_read_b128 v[64:67], v159
	ds_read_b128 v[68:71], v159 offset:4352
	ds_read_b128 v[72:75], v159 offset:8704
	ds_read_b128 v[76:79], v159 offset:13056
	s_waitcnt lgkmcnt(3)
	v_mfma_f32_16x16x32_bf16 v[64:67], v[60:63], v[64:67], 0
	s_nop 1
	s_waitcnt lgkmcnt(2)
	v_mfma_f32_16x16x32_bf16 v[68:71], v[60:63], v[68:71], 0
	s_waitcnt lgkmcnt(1)
	v_mfma_f32_16x16x32_bf16 v[72:75], v[60:63], v[72:75], 0
	s_waitcnt lgkmcnt(0)
	v_mfma_f32_16x16x32_bf16 v[60:63], v[60:63], v[76:79], 0
	ds_read_b128 v[76:79], v157 offset:64
	ds_read_b128 v[80:83], v160
	ds_read_b128 v[84:87], v160 offset:4352
	ds_read_b128 v[88:91], v160 offset:8704
	ds_read_b128 v[92:95], v160 offset:13056
	s_waitcnt lgkmcnt(3)
	v_mfma_f32_16x16x32_bf16 v[64:67], v[76:79], v[80:83], v[64:67]
	s_waitcnt lgkmcnt(2)
	v_mfma_f32_16x16x32_bf16 v[68:71], v[76:79], v[84:87], v[68:71]
	s_waitcnt lgkmcnt(1)
	v_mfma_f32_16x16x32_bf16 v[72:75], v[76:79], v[88:91], v[72:75]
	s_waitcnt lgkmcnt(0)
	v_mfma_f32_16x16x32_bf16 v[60:63], v[76:79], v[92:95], v[60:63]
	ds_read_b128 v[76:79], v157 offset:128
	ds_read_b128 v[80:83], v161
	ds_read_b128 v[84:87], v161 offset:4352
	ds_read_b128 v[88:91], v161 offset:8704
	ds_read_b128 v[92:95], v161 offset:13056
	s_waitcnt lgkmcnt(3)
	v_mfma_f32_16x16x32_bf16 v[64:67], v[76:79], v[80:83], v[64:67]
	s_waitcnt lgkmcnt(2)
	v_mfma_f32_16x16x32_bf16 v[68:71], v[76:79], v[84:87], v[68:71]
	s_waitcnt lgkmcnt(1)
	v_mfma_f32_16x16x32_bf16 v[80:83], v[76:79], v[88:91], v[72:75]
	s_waitcnt lgkmcnt(0)
	v_mfma_f32_16x16x32_bf16 v[60:63], v[76:79], v[92:95], v[60:63]
	ds_read_b128 v[76:79], v157 offset:192
	ds_read_b128 v[72:75], v162
	ds_read_b128 v[84:87], v162 offset:4352
	ds_read_b128 v[88:91], v162 offset:8704
	ds_read_b128 v[92:95], v162 offset:13056
	s_waitcnt lgkmcnt(3)
	v_mfma_f32_16x16x32_bf16 v[72:75], v[76:79], v[72:75], v[64:67]
	s_waitcnt lgkmcnt(2)
	v_mfma_f32_16x16x32_bf16 v[68:71], v[76:79], v[84:87], v[68:71]
	s_nop 2
	s_waitcnt lgkmcnt(1)
	v_mfma_f32_16x16x32_bf16 v[64:67], v[76:79], v[88:91], v[80:83]
	s_waitcnt lgkmcnt(0)
	v_mfma_f32_16x16x32_bf16 v[60:63], v[76:79], v[92:95], v[60:63]
	v_cvt_pk_bf16_f32 v3, v34, v35
	v_cvt_pk_bf16_f32 v2, v32, v33
	v_cvt_pk_bf16_f32 v77, v30, v31
	v_cvt_pk_bf16_f32 v76, v28, v29
	v_cvt_pk_bf16_f32 v79, v26, v27
	v_cvt_pk_bf16_f32 v78, v24, v25
	v_cvt_pk_bf16_f32 v81, v22, v23
	v_cvt_pk_bf16_f32 v80, v20, v21
	v_cvt_pk_bf16_f32 v83, v18, v19
	v_cvt_pk_bf16_f32 v82, v16, v17
	v_add_u32_e32 v84, 0xb000, v216
	ds_write2_b64 v84, v[2:3], v[82:83] offset1:4
	v_cvt_pk_bf16_f32 v3, v14, v15
	v_cvt_pk_bf16_f32 v2, v12, v13
	v_add_u32_e32 v82, 0xc000, v216
	ds_write2_b64 v82, v[76:77], v[2:3] offset0:32 offset1:36
	v_cvt_pk_bf16_f32 v3, v10, v11
	v_cvt_pk_bf16_f32 v2, v8, v9
	v_add_u32_e32 v76, 0xd000, v216
	ds_write2_b64 v76, v[78:79], v[2:3] offset0:64 offset1:68
	v_cvt_pk_bf16_f32 v3, v6, v7
	v_cvt_pk_bf16_f32 v2, v4, v5
	v_add_u32_e32 v76, 0xe000, v216
	ds_write2_b64 v76, v[80:81], v[2:3] offset0:96 offset1:100
	v_mov_b32_e32 v2, 0
	v_mov_b32_e32 v3, 0
	s_waitcnt lgkmcnt(0)
	s_barrier
	ds_read_b32 v228, v168
	ds_read_b32 v229, v166
	ds_read_b32 v230, v167
	ds_read_b32 v231, v171
	ds_read_b32 v232, v173
	ds_read_b32 v233, v175
	ds_read_b32 v234, v176
	ds_read_b32 v235, v177
	ds_read_b32 v236, v182
	ds_read_b32 v237, v183
	ds_read_b32 v238, v188
	ds_read_b32 v239, v189
	s_waitcnt lgkmcnt(0)
	s_and_saveexec_b64 s[54:55], s[20:21]
	s_cbranch_execz .LBB0_1710
	v_mov_b32_e32 v3, v228
	v_mov_b32_e32 v76, v229
	v_sub_f32_e32 v3, v3, v76
	v_mul_f32_e32 v3, 0x3fb8aa3b, v3
	v_exp_f32_e32 v3, v3
	s_nop 0
	v_mul_f32_e32 v3, v72, v3
	v_mov_b32_e32 v72, v230
	v_mul_f32_e32 v3, v72, v3
.LBB0_1710:
	s_or_b64 exec, exec, s[54:55]
	v_bfe_u32 v72, v3, 16, 1
	v_add3_u32 v3, v3, v72, s85
	v_add_u32_e32 v72, v127, v169
	ds_write_b16_d16_hi v72, v3
	s_and_saveexec_b64 s[54:55], s[22:23]
	s_cbranch_execz .LBB0_1712
	v_mov_b32_e32 v2, v231
	v_mov_b32_e32 v3, v229
	v_sub_f32_e32 v2, v2, v3
	v_mul_f32_e32 v2, 0x3fb8aa3b, v2
	v_exp_f32_e32 v2, v2
	v_mov_b32_e32 v3, v230
	v_mul_f32_e32 v2, v73, v2
	v_mul_f32_e32 v2, v3, v2
.LBB0_1712:
	s_or_b64 exec, exec, s[54:55]
	v_bfe_u32 v3, v2, 16, 1
	v_add3_u32 v2, v2, v3, s85
	ds_write_b16_d16_hi v217, v2
	v_mov_b32_e32 v2, 0
	v_mov_b32_e32 v3, 0
	s_and_saveexec_b64 s[54:55], s[24:25]
	s_cbranch_execz .LBB0_1714
	v_mov_b32_e32 v3, v232
	v_mov_b32_e32 v72, v229
	v_sub_f32_e32 v3, v3, v72
	v_mul_f32_e32 v3, 0x3fb8aa3b, v3
	v_exp_f32_e32 v3, v3
	v_mov_b32_e32 v72, v230
	v_mul_f32_e32 v3, v74, v3
	v_mul_f32_e32 v3, v72, v3
.LBB0_1714:
	s_or_b64 exec, exec, s[54:55]
	v_bfe_u32 v72, v3, 16, 1
	v_add3_u32 v3, v3, v72, s85
	ds_write_b16_d16_hi v218, v3
	s_and_saveexec_b64 s[54:55], s[26:27]
	s_cbranch_execz .LBB0_1716
	v_mov_b32_e32 v2, v233
	v_mov_b32_e32 v3, v229
	v_sub_f32_e32 v2, v2, v3
	v_mul_f32_e32 v2, 0x3fb8aa3b, v2
	v_exp_f32_e32 v2, v2
	v_mov_b32_e32 v3, v230
	v_mul_f32_e32 v2, v75, v2
	v_mul_f32_e32 v2, v3, v2
.LBB0_1716:
	s_or_b64 exec, exec, s[54:55]
	v_bfe_u32 v3, v2, 16, 1
	v_add3_u32 v2, v2, v3, s85
	ds_write_b16_d16_hi v219, v2
	v_mov_b32_e32 v2, 0
	v_mov_b32_e32 v3, 0
	s_and_saveexec_b64 s[54:55], s[28:29]
	s_cbranch_execz .LBB0_1718
	v_mov_b32_e32 v3, v228
	v_mov_b32_e32 v72, v234
	v_sub_f32_e32 v3, v3, v72
	v_mul_f32_e32 v3, 0x3fb8aa3b, v3
	v_exp_f32_e32 v3, v3
	s_nop 0
	v_mul_f32_e32 v3, v68, v3
	v_mov_b32_e32 v68, v235
	v_mul_f32_e32 v3, v68, v3
.LBB0_1718:
	s_or_b64 exec, exec, s[54:55]
	v_bfe_u32 v68, v3, 16, 1
	v_add3_u32 v3, v3, v68, s85
	ds_write_b16_d16_hi v178, v3
	s_and_saveexec_b64 s[54:55], s[30:31]
	s_cbranch_execz .LBB0_1720
	v_mov_b32_e32 v2, v231
	v_mov_b32_e32 v3, v234
	v_sub_f32_e32 v2, v2, v3
	v_mul_f32_e32 v2, 0x3fb8aa3b, v2
	v_exp_f32_e32 v2, v2
	v_mov_b32_e32 v3, v235
	v_mul_f32_e32 v2, v69, v2
	v_mul_f32_e32 v2, v3, v2
.LBB0_1720:
	s_or_b64 exec, exec, s[54:55]
	v_bfe_u32 v3, v2, 16, 1
	v_add3_u32 v2, v2, v3, s85
	ds_write_b16_d16_hi v179, v2
	v_mov_b32_e32 v2, 0
	v_mov_b32_e32 v3, 0
	s_and_saveexec_b64 s[54:55], s[34:35]
	s_cbranch_execz .LBB0_1722
	v_mov_b32_e32 v3, v232
	v_mov_b32_e32 v68, v234
	v_sub_f32_e32 v3, v3, v68
	v_mul_f32_e32 v3, 0x3fb8aa3b, v3
	v_exp_f32_e32 v3, v3
	v_mov_b32_e32 v68, v235
	v_mul_f32_e32 v3, v70, v3
	v_mul_f32_e32 v3, v68, v3
.LBB0_1722:
	s_or_b64 exec, exec, s[54:55]
	v_bfe_u32 v68, v3, 16, 1
	v_add3_u32 v3, v3, v68, s85
	ds_write_b16_d16_hi v180, v3
	s_and_saveexec_b64 s[54:55], s[36:37]
	s_cbranch_execz .LBB0_1724
	v_mov_b32_e32 v2, v233
	v_mov_b32_e32 v3, v234
	v_sub_f32_e32 v2, v2, v3
	v_mul_f32_e32 v2, 0x3fb8aa3b, v2
	v_exp_f32_e32 v2, v2
	v_mov_b32_e32 v3, v235
	v_mul_f32_e32 v2, v71, v2
	v_mul_f32_e32 v2, v3, v2
.LBB0_1724:
	s_or_b64 exec, exec, s[54:55]
	v_bfe_u32 v3, v2, 16, 1
	v_add3_u32 v2, v2, v3, s85
	ds_write_b16_d16_hi v181, v2
	v_mov_b32_e32 v2, 0
	v_mov_b32_e32 v3, 0
	s_and_saveexec_b64 s[54:55], s[38:39]
	s_cbranch_execz .LBB0_1726
	v_mov_b32_e32 v3, v228
	v_mov_b32_e32 v68, v236
	v_sub_f32_e32 v3, v3, v68
	v_mul_f32_e32 v3, 0x3fb8aa3b, v3
	v_exp_f32_e32 v3, v3
	s_nop 0
	v_mul_f32_e32 v3, v64, v3
	v_mov_b32_e32 v64, v237
	v_mul_f32_e32 v3, v64, v3
.LBB0_1726:
	s_or_b64 exec, exec, s[54:55]
	v_bfe_u32 v64, v3, 16, 1
	v_add3_u32 v3, v3, v64, s85
	ds_write_b16_d16_hi v184, v3
	s_and_saveexec_b64 s[54:55], s[40:41]
	s_cbranch_execz .LBB0_1728
	v_mov_b32_e32 v2, v231
	v_mov_b32_e32 v3, v236
	v_sub_f32_e32 v2, v2, v3
	v_mul_f32_e32 v2, 0x3fb8aa3b, v2
	v_exp_f32_e32 v2, v2
	v_mov_b32_e32 v3, v237
	v_mul_f32_e32 v2, v65, v2
	v_mul_f32_e32 v2, v3, v2
.LBB0_1728:
	s_or_b64 exec, exec, s[54:55]
	v_bfe_u32 v3, v2, 16, 1
	v_add3_u32 v2, v2, v3, s85
	ds_write_b16_d16_hi v185, v2
	v_mov_b32_e32 v2, 0
	v_mov_b32_e32 v3, 0
	s_and_saveexec_b64 s[54:55], s[42:43]
	s_cbranch_execz .LBB0_1730
	v_mov_b32_e32 v3, v232
	v_mov_b32_e32 v64, v236
	v_sub_f32_e32 v3, v3, v64
	v_mul_f32_e32 v3, 0x3fb8aa3b, v3
	v_exp_f32_e32 v3, v3
	v_mov_b32_e32 v64, v237
	v_mul_f32_e32 v3, v66, v3
	v_mul_f32_e32 v3, v64, v3
.LBB0_1730:
	s_or_b64 exec, exec, s[54:55]
	v_bfe_u32 v64, v3, 16, 1
	v_add3_u32 v3, v3, v64, s85
	ds_write_b16_d16_hi v186, v3
	s_and_saveexec_b64 s[54:55], s[44:45]
	s_cbranch_execz .LBB0_1732
	v_mov_b32_e32 v2, v233
	v_mov_b32_e32 v3, v236
	v_sub_f32_e32 v2, v2, v3
	v_mul_f32_e32 v2, 0x3fb8aa3b, v2
	v_exp_f32_e32 v2, v2
	v_mov_b32_e32 v3, v237
	v_mul_f32_e32 v2, v67, v2
	v_mul_f32_e32 v2, v3, v2
.LBB0_1732:
	s_or_b64 exec, exec, s[54:55]
	v_bfe_u32 v3, v2, 16, 1
	v_add3_u32 v2, v2, v3, s85
	ds_write_b16_d16_hi v187, v2
	v_mov_b32_e32 v2, 0
	v_mov_b32_e32 v3, 0
	s_and_saveexec_b64 s[54:55], s[46:47]
	s_cbranch_execz .LBB0_1734
	v_mov_b32_e32 v3, v228
	v_mov_b32_e32 v64, v238
	v_sub_f32_e32 v3, v3, v64
	v_mul_f32_e32 v3, 0x3fb8aa3b, v3
	v_exp_f32_e32 v3, v3
	s_nop 0
	v_mul_f32_e32 v3, v60, v3
	v_mov_b32_e32 v60, v239
	v_mul_f32_e32 v3, v60, v3
.LBB0_1734:
	s_or_b64 exec, exec, s[54:55]
	v_bfe_u32 v60, v3, 16, 1
	v_add3_u32 v3, v3, v60, s85
	ds_write_b16_d16_hi v192, v3
	s_and_saveexec_b64 s[54:55], s[48:49]
	s_cbranch_execz .LBB0_1736
	v_mov_b32_e32 v2, v231
	v_mov_b32_e32 v3, v238
	v_sub_f32_e32 v2, v2, v3
	v_mul_f32_e32 v2, 0x3fb8aa3b, v2
	v_exp_f32_e32 v2, v2
	v_mov_b32_e32 v3, v239
	v_mul_f32_e32 v2, v61, v2
	v_mul_f32_e32 v2, v3, v2
.LBB0_1736:
	s_or_b64 exec, exec, s[54:55]
	v_bfe_u32 v3, v2, 16, 1
	v_add3_u32 v2, v2, v3, s85
	ds_write_b16_d16_hi v193, v2
	v_mov_b32_e32 v2, 0
	v_mov_b32_e32 v3, 0
	s_and_saveexec_b64 s[54:55], s[50:51]
	s_cbranch_execz .LBB0_1738
	v_mov_b32_e32 v3, v232
	v_mov_b32_e32 v60, v238
	v_sub_f32_e32 v3, v3, v60
	v_mul_f32_e32 v3, 0x3fb8aa3b, v3
	v_exp_f32_e32 v3, v3
	v_mov_b32_e32 v60, v239
	v_mul_f32_e32 v3, v62, v3
	v_mul_f32_e32 v3, v60, v3
.LBB0_1738:
	s_or_b64 exec, exec, s[54:55]
	v_bfe_u32 v60, v3, 16, 1
	v_add3_u32 v3, v3, v60, s85
	ds_write_b16_d16_hi v194, v3
	s_and_saveexec_b64 s[54:55], s[52:53]
	s_cbranch_execz .LBB0_1740
	v_mov_b32_e32 v2, v233
	v_mov_b32_e32 v3, v238
	v_sub_f32_e32 v2, v2, v3
	v_mul_f32_e32 v2, 0x3fb8aa3b, v2
	v_exp_f32_e32 v2, v2
	v_mov_b32_e32 v3, v239
	v_mul_f32_e32 v2, v63, v2
	v_mul_f32_e32 v2, v3, v2
